# flat release poll plus: XCD leaders no longer publish the per-XCD generation word nobody reads (one atomic less before their closing wait)
# baseline (speedup 1.0000x reference)
.LBB0_92:
	s_or_b64 exec, exec, s[8:9]
	s_mov_b64 s[8:9], exec
	v_mbcnt_lo_u32_b32 v0, s8, 0
	v_mbcnt_hi_u32_b32 v0, s9, v0
	v_cmp_eq_u32_e32 vcc, 0, v0
	s_waitcnt vmcnt(0)
	buffer_inv sc1
	s_and_saveexec_b64 s[10:11], vcc
	s_cbranch_execz .LBB0_94
	s_bcnt1_i32_b64 s8, s[8:9]
	v_mov_b32_e32 v0, 0x2000
	v_mov_b32_e32 v1, s8
	s_nop 0

.LBB0_212:
	s_or_b64 exec, exec, s[6:7]
	s_mov_b64 s[6:7], exec
	v_mbcnt_lo_u32_b32 v0, s6, 0
	v_mbcnt_hi_u32_b32 v0, s7, v0
	v_cmp_eq_u32_e32 vcc, 0, v0
	s_waitcnt vmcnt(0)
	buffer_inv sc1
	s_and_saveexec_b64 s[8:9], vcc
	s_cbranch_execz .LBB0_214
	s_bcnt1_i32_b64 s6, s[6:7]
	v_mov_b32_e32 v0, 0x2000
	v_mov_b32_e32 v1, s6
	s_nop 0

.LBB0_453:
	s_or_b64 exec, exec, s[4:5]
	s_mov_b64 s[4:5], exec
	v_mbcnt_lo_u32_b32 v0, s4, 0
	v_mbcnt_hi_u32_b32 v0, s5, v0
	v_cmp_eq_u32_e32 vcc, 0, v0
	s_waitcnt vmcnt(0)
	buffer_inv sc1
	s_and_saveexec_b64 s[6:7], vcc
	s_cbranch_execz .LBB0_455
	s_bcnt1_i32_b64 s4, s[4:5]
	v_mov_b32_e32 v0, 0x2000
	v_mov_b32_e32 v1, s4
	s_nop 0
